# instruction-fetch alignment extended to the natten and dilated inner loop headers (64-byte aligned)
# baseline (speedup 1.0000x reference)
; __global__ void __launch_bounds__(NT) fwd_megakernel(Params P) {
;     ...
;     for (int layer = 0; layer < 4; ++layer) {
;         const bool even = !(layer & 1); const int j = layer >> 1;
;         bf16_t* HBUF = (bf16_t*)P.out;
.Lhop_lbb8:
	s_branch .LBB0_8
	.p2align	6

; #define LAS __attribute__((address_space(3)))
;     __device__ __forceinline__ int qtok(int n) const { return (r0 + (n >> 4)) * 64 + c0 + (n & 15); }
; __device__ __forceinline__ void natten_wave_task2(const bf16_t* __restrict__ proj, int b, int h, NatPol pA, NatPol pB, bf16_t* __restrict__ yout, int lane, LAS unsigned char* wl) {
;     const int r = lane & 31, hh = lane >> 5, xaddr = (lane ^ 32) << 2;
;     pA.init(r, hh); pB.init(r, hh);
;     const int qtA = pA.qtok(r), qtB = pB.qtok(r);
;     const bf16_t* qbase = proj + (size_t)(b * 16 + h) * (4096 * 64); const bf16_t* kbase = qbase + (size_t)T_TOK * 1024; const bf16_t* vbase = kbase + (size_t)T_TOK * 1024; const bf16_t* gbase = vbase + (size_t)T_TOK * 1024;
;     bf16x8s qA[4], qB[4];
; #pragma unroll
;     for (int s = 0; s < 4; ++s) { qA[s] = *(const bf16x8s*)(qbase + qtA * 64 + 16 * s + 8 * hh); qB[s] = *(const bf16x8s*)(qbase + qtB * 64 + 16 * s + 8 * hh); }
;     f32x16 oA0, oA1, oB0, oB1;
; #pragma unroll
;     for (int i = 0; i < 16; ++i) { oA0[i] = 0.f; oA1[i] = 0.f; oB0[i] = 0.f; oB1[i] = 0.f; }
;     float mA = -40.0f, lA = 0.f, mB = -40.0f, lB = 0.f;
;     constexpr int NB = 11;
;     bf16x8s kf[4]; u32x4a vg[4];
;     attn_loadk<NatPol>(kbase, pA, 0, r, hh, kf);
;     attn_loadv<NatPol>(vbase, pA, 0, r, hh, vg);
.Lnat1_nobar2:
	s_add_u32 s14, s6, 0x4000000
	v_lshl_add_u64 v[2:3], v[2:3], 0, v[192:193]
	global_load_dwordx4 v[96:99], v[0:1], off
	global_load_dwordx4 v[100:103], v[0:1], off offset:32
	global_load_dwordx4 v[104:107], v[2:3], off
	global_load_dwordx4 v[108:111], v[2:3], off offset:32
	global_load_dwordx4 v[112:115], v[0:1], off offset:64
	global_load_dwordx4 v[116:119], v[0:1], off offset:96
	global_load_dwordx4 v[120:123], v[2:3], off offset:64
	global_load_dwordx4 v[124:127], v[2:3], off offset:96
	v_lshlrev_b32_e32 v211, 12, v207
	s_addc_u32 s15, s7, 0
	v_add_lshl_u32 v0, v211, v181, 1
	v_mov_b32_e32 v1, v193
	v_lshl_add_u64 v[0:1], s[14:15], 0, v[0:1]
	v_lshl_add_u64 v[0:1], v[0:1], 0, v[192:193]
	v_cmp_lt_i32_e32 vcc, 3, v4
	v_mov_b32_e32 v163, v193
	v_lshl_add_u64 v[0:1], s[6:7], 0, v[162:163]
	v_cndmask_b32_e32 v208, 0, v5, vcc
	v_cmp_lt_i32_e32 vcc, 3, v6
	s_mov_b64 s[18:19], 0x8000000
	v_lshl_add_u64 v[170:171], v[0:1], 0, s[18:19]
	s_mov_b64 s[18:19], 0x4000000
	v_lshl_add_u64 v[240:241], v[0:1], 0, s[18:19]
	v_lshrrev_b32_e32 v242, 6, v195
	v_mul_u32_u24_e32 v242, 0x1200, v242
	v_and_b32_e32 v243, 31, v195
	v_mul_u32_u24_e32 v243, 0x90, v243
	v_add_u32_e32 v242, v242, v243
	v_bfe_u32 v243, v195, 5, 1
	v_lshl_add_u32 v242, v243, 4, v242
	v_add_u32_e32 v242, 0x9000, v242
	v_add_u32_e32 v243, 0x9000, v190
	v_add_u32_e32 v200, v211, v182
	v_or_b32_e32 v202, v211, v183
	v_ashrrev_i32_e32 v201, 31, v200
	v_ashrrev_i32_e32 v203, 31, v202
	v_lshl_add_u64 v[200:201], v[200:201], 1, v[240:241]
	v_lshl_add_u64 v[202:203], v[202:203], 1, v[240:241]
	global_load_dwordx4 v[140:143], v[200:201], off
	global_load_dwordx4 v[136:139], v[202:203], off
	v_add_u32_e32 v200, v211, v184
	v_add_u32_e32 v202, v211, v185
	v_ashrrev_i32_e32 v201, 31, v200
	v_ashrrev_i32_e32 v203, 31, v202
	v_lshl_add_u64 v[200:201], v[200:201], 1, v[240:241]
	v_lshl_add_u64 v[202:203], v[202:203], 1, v[240:241]
	global_load_dwordx4 v[132:135], v[200:201], off
	global_load_dwordx4 v[128:131], v[202:203], off
	v_add_u32_e32 v200, v211, v182
	v_or_b32_e32 v202, v211, v183
	v_ashrrev_i32_e32 v201, 31, v200
	v_ashrrev_i32_e32 v203, 31, v202
	v_lshl_add_u64 v[200:201], v[200:201], 1, v[170:171]
	v_lshl_add_u64 v[202:203], v[202:203], 1, v[170:171]
	global_load_dwordx4 v[144:147], v[200:201], off
	global_load_dwordx4 v[148:151], v[202:203], off
	v_add_u32_e32 v200, v211, v184
	v_add_u32_e32 v202, v211, v185
	v_ashrrev_i32_e32 v201, 31, v200
	v_ashrrev_i32_e32 v203, 31, v202
	v_lshl_add_u64 v[200:201], v[200:201], 1, v[170:171]
	v_lshl_add_u64 v[202:203], v[202:203], 1, v[170:171]
	global_load_dwordx4 v[152:155], v[200:201], off
	global_load_dwordx4 v[156:159], v[202:203], off
	v_cndmask_b32_e32 v209, 0, v7, vcc
	v_mov_b32_e32 v0, 0
	s_mov_b32 s10, -4
	s_mov_b32 s11, 0
	v_lshl_add_u64 v[172:173], s[14:15], 0, v[192:193]
	v_add_u32_e32 v163, 8, v208
	v_add_u32_e32 v210, 8, v209
	v_mov_b32_e32 v212, 0xc2200000
	v_mov_b32_e32 v213, 0xc2200000
	v_mov_b32_e32 v1, v0
	v_mov_b32_e32 v2, v0
	v_mov_b32_e32 v3, v0
	v_mov_b32_e32 v4, v0
	v_mov_b32_e32 v5, v0
	v_mov_b32_e32 v6, v0
	v_mov_b32_e32 v7, v0
	v_mov_b32_e32 v8, v0
	v_mov_b32_e32 v9, v0
	v_mov_b32_e32 v10, v0
	v_mov_b32_e32 v11, v0
	v_mov_b32_e32 v12, v0
	v_mov_b32_e32 v13, v0
	v_mov_b32_e32 v14, v0
	v_mov_b32_e32 v15, v0
	v_mov_b32_e32 v16, v0
	v_mov_b32_e32 v17, v0
	v_mov_b32_e32 v18, v0
	v_mov_b32_e32 v19, v0
	v_mov_b32_e32 v20, v0
	v_mov_b32_e32 v21, v0
	v_mov_b32_e32 v22, v0
	v_mov_b32_e32 v23, v0
	v_mov_b32_e32 v24, v0
	v_mov_b32_e32 v25, v0
	v_mov_b32_e32 v26, v0
	v_mov_b32_e32 v27, v0
	v_mov_b32_e32 v28, v0
	v_mov_b32_e32 v29, v0
	v_mov_b32_e32 v30, v0
	v_mov_b32_e32 v31, v0
	v_mov_b32_e32 v32, v0
	v_mov_b32_e32 v33, v0
	v_mov_b32_e32 v34, v0
	v_mov_b32_e32 v35, v0
	v_mov_b32_e32 v36, v0
	v_mov_b32_e32 v37, v0
	v_mov_b32_e32 v38, v0
	v_mov_b32_e32 v39, v0
	v_mov_b32_e32 v40, v0
	v_mov_b32_e32 v41, v0
	v_mov_b32_e32 v42, v0
	v_mov_b32_e32 v43, v0
	v_mov_b32_e32 v44, v0
	v_mov_b32_e32 v45, v0
	v_mov_b32_e32 v46, v0
	v_mov_b32_e32 v47, v0
	v_mov_b32_e32 v48, v0
	v_mov_b32_e32 v49, v0
	v_mov_b32_e32 v50, v0
	v_mov_b32_e32 v51, v0
	v_mov_b32_e32 v52, v0
	v_mov_b32_e32 v53, v0
	v_mov_b32_e32 v54, v0
	v_mov_b32_e32 v55, v0
	v_mov_b32_e32 v56, v0
	v_mov_b32_e32 v57, v0
	v_mov_b32_e32 v58, v0
	v_mov_b32_e32 v59, v0
	v_mov_b32_e32 v60, v0
	v_mov_b32_e32 v61, v0
	v_mov_b32_e32 v62, v0
	v_mov_b32_e32 v63, v0
	v_mov_b32_e32 v174, v0
	v_mov_b32_e32 v175, v0
	s_branch .LBB0_574
	.p2align	6

;     __device__ __forceinline__ int qtok(int n) const { return (r0 + (n >> 4)) * 64 + c0 + (n & 15); }
; template <class Pol, int MODE>
; __device__ __forceinline__ void attn_wave_task(const bf16_t* __restrict__ proj, int b, int h, Pol pol, bf16_t* __restrict__ yout, int lane, float* __restrict__ X, LAS unsigned char* wl) {
;     const int r = lane & 31, hh = lane >> 5, xaddr = (lane ^ 32) << 2;
;     pol.init(r, hh);
;     const int qt = pol.qtok(r);
;     const bf16_t* qbase = proj + (size_t)(b * 16 + h) * (4096 * 64); const bf16_t* kbase = qbase + (size_t)T_TOK * 1024; const bf16_t* vbase = kbase + (size_t)T_TOK * 1024; const bf16_t* gbase = vbase + (size_t)T_TOK * 1024;
;     bf16x8s qf[4];
; #pragma unroll
;     for (int s = 0; s < 4; ++s) qf[s] = *(const bf16x8s*)(qbase + qt * 64 + 16 * s + 8 * hh);
;     f32x16 o0, o1;
;     float m_run = -40.0f, l_run = 0.f;
;     if (MODE == 2) { const float* xr = X + (size_t)pol.xrow(r) * 68;
; #pragma unroll
;         for (int g = 0; g < 4; ++g) { const float4 a0 = *(const float4*)(xr + 8 * g + 4 * hh), a1 = *(const float4*)(xr + 32 + 8 * g + 4 * hh);
;             o0[4 * g] = a0.x; o0[4 * g + 1] = a0.y; o0[4 * g + 2] = a0.z; o0[4 * g + 3] = a0.w; o1[4 * g] = a1.x; o1[4 * g + 1] = a1.y; o1[4 * g + 2] = a1.z; o1[4 * g + 3] = a1.w; }
;         m_run = xr[64]; l_run = hh == 0 ? xr[65] : 0.f;
;     } else {
; #pragma unroll
;         for (int i = 0; i < 16; ++i) { o0[i] = 0.f; o1[i] = 0.f; } }
;     constexpr int NB = Pol::NB;
;     bf16x8s kf[4]; u32x4a vfA[4];
;     attn_loadk<Pol>(kbase, pol, 0, r, hh, kf);
;     attn_loadv<Pol>(vbase, pol, 0, r, hh, vfA);
; #pragma unroll 1
;     for (int fb = 0; fb < NB; ++fb)
;         attn_compute<Pol>(kbase, pol, fb, fb + 1 < NB ? fb + 1 : NB - 1, (MODE != 2) && (fb == 0), r, hh, xaddr, qf, kf, vfA, vbase, wl, o0, o1, m_run, l_run);
;     __device__ __forceinline__ int ktok(int fb, int ks) const { int t = t0 + stride(fb) * (-64 + 32 * kbof(fb) + ks); t = t < 0 ? 0 : (t > SEQ - 1 ? SEQ - 1 : t); return t; }
.LBB0_590:
	v_or_b32_e32 v97, s23, v150
	v_add_u32_e32 v98, s30, v97
	v_add_lshl_u32 v0, v98, v152, 6
	v_ashrrev_i32_e32 v1, 31, v0
	v_lshl_add_u64 v[0:1], v[0:1], 1, v[120:121]
	global_load_dwordx4 v[48:51], v[0:1], off
	global_load_dwordx4 v[52:55], v[0:1], off offset:32
	global_load_dwordx4 v[56:59], v[0:1], off offset:64
	global_load_dwordx4 v[60:63], v[0:1], off offset:96
	v_add_u32_e32 v0, v98, v155
	v_med3_i32 v0, v0, 0, v248
	v_lshlrev_b32_e32 v192, 7, v0
	v_lshl_add_u64 v[0:1], v[122:123], 0, v[192:193]
	global_load_dwordx4 v[92:95], v[0:1], off
	global_load_dwordx4 v[88:91], v[0:1], off offset:32
	global_load_dwordx4 v[84:87], v[0:1], off offset:64
	global_load_dwordx4 v[80:83], v[0:1], off offset:96
	v_add_u32_e32 v0, v157, v98
	v_med3_i32 v0, v0, 0, v248
	v_add_u32_e32 v2, v158, v98
	v_lshlrev_b32_e32 v192, 7, v0
	v_med3_i32 v2, v2, 0, v248
	v_lshl_add_u64 v[0:1], v[124:125], 0, v[192:193]
	v_lshlrev_b32_e32 v192, 7, v2
	v_lshl_add_u64 v[2:3], v[124:125], 0, v[192:193]
	global_load_dwordx4 v[68:71], v[0:1], off
	global_load_dwordx4 v[64:67], v[2:3], off
	v_add_u32_e32 v0, v159, v98
	v_med3_i32 v0, v0, 0, v248
	v_add_u32_e32 v2, v160, v98
	v_lshlrev_b32_e32 v192, 7, v0
	v_med3_i32 v2, v2, 0, v248
	v_lshl_add_u64 v[0:1], v[124:125], 0, v[192:193]
	v_lshlrev_b32_e32 v192, 7, v2
	v_lshl_add_u64 v[2:3], v[124:125], 0, v[192:193]
	global_load_dwordx4 v[72:75], v[0:1], off
	global_load_dwordx4 v[76:79], v[2:3], off
	v_mov_b32_e32 v99, 0
	s_mov_b64 s[64:65], s[96:97]
	s_xor_b64 s[14:15], s[10:11], -1
	v_mov_b32_e32 v96, 0xc2200000
	s_movk_i32 s10, 0xff60
	s_mov_b32 s11, 0
	v_mov_b32_e32 v0, 0
	v_mov_b32_e32 v1, v99
	v_mov_b32_e32 v2, v99
	v_mov_b32_e32 v3, v99
	v_mov_b32_e32 v4, v99
	v_mov_b32_e32 v5, v99
	v_mov_b32_e32 v6, v99
	v_mov_b32_e32 v7, v99
	v_mov_b32_e32 v8, v99
	v_mov_b32_e32 v9, v99
	v_mov_b32_e32 v10, v99
	v_mov_b32_e32 v11, v99
	v_mov_b32_e32 v12, v99
	v_mov_b32_e32 v13, v99
	v_mov_b32_e32 v14, v99
	v_mov_b32_e32 v15, v99
	v_mov_b32_e32 v16, 0
	v_mov_b32_e32 v17, v99
	v_mov_b32_e32 v18, v99
	v_mov_b32_e32 v19, v99
	v_mov_b32_e32 v20, v99
	v_mov_b32_e32 v21, v99
	v_mov_b32_e32 v22, v99
	v_mov_b32_e32 v23, v99
	v_mov_b32_e32 v24, v99
	v_mov_b32_e32 v25, v99
	v_mov_b32_e32 v26, v99
	v_mov_b32_e32 v27, v99
	v_mov_b32_e32 v28, v99
	v_mov_b32_e32 v29, v99
	v_mov_b32_e32 v30, v99
	v_mov_b32_e32 v31, v99
	s_branch .LBB0_592
	.p2align	6

; __device__ __forceinline__ void attn_store_out(const f32x16& o0, const f32x16& o1, float inv, const bf16_t* __restrict__ gbase, int qt, bf16_t* __restrict__ yout, int b, int h, int hh) {
;     ...
;         for (int g = 0; g < 4; ++g) gws[dt][g] = *(const uint2*)(gbase + qt * 64 + dt * 32 + 8 * g + 4 * hh);
; template <class Pol, int MODE>
; __device__ __forceinline__ void attn_wave_task(const bf16_t* __restrict__ proj, int b, int h, Pol pol, bf16_t* __restrict__ yout, int lane, float* __restrict__ X, LAS unsigned char* wl) {
;     ...
;     constexpr int NB = Pol::NB;
;     bf16x8s kf[4]; u32x4a vfA[4];
;     attn_loadk<Pol>(kbase, pol, 0, r, hh, kf);
;     attn_loadv<Pol>(vbase, pol, 0, r, hh, vfA);
.LBB0_599:
	s_or_b64 exec, exec, s[6:7]
	v_subrev_u32_e32 v34, 64, v173
	v_or_b32_e32 v175, v34, v151
	v_med3_i32 v32, v175, 0, v248
	v_lshlrev_b32_e32 v192, 7, v32
	v_lshl_add_u64 v[32:33], v[122:123], 0, v[192:193]
	global_load_dwordx4 v[92:95], v[32:33], off
	global_load_dwordx4 v[72:75], v[32:33], off offset:32
	global_load_dwordx4 v[68:71], v[32:33], off offset:64
	global_load_dwordx4 v[64:67], v[32:33], off offset:96
	v_or_b32_e32 v32, v34, v156
	v_med3_i32 v32, v32, 0, v248
	v_add_u32_e32 v34, v163, v173
	v_lshlrev_b32_e32 v192, 7, v32
	v_med3_i32 v34, v34, 0, v248
	v_lshl_add_u64 v[32:33], v[124:125], 0, v[192:193]
	v_lshlrev_b32_e32 v192, 7, v34
	v_lshl_add_u64 v[34:35], v[124:125], 0, v[192:193]
	global_load_dwordx4 v[76:79], v[32:33], off
	global_load_dwordx4 v[80:83], v[34:35], off
	v_add_u32_e32 v32, v164, v173
	v_med3_i32 v32, v32, 0, v248
	v_add_u32_e32 v34, v165, v173
	v_lshlrev_b32_e32 v192, 7, v32
	v_med3_i32 v34, v34, 0, v248
	v_lshl_add_u64 v[32:33], v[124:125], 0, v[192:193]
	v_lshlrev_b32_e32 v192, 7, v34
	v_lshl_add_u64 v[34:35], v[124:125], 0, v[192:193]
	global_load_dwordx4 v[84:87], v[32:33], off
	global_load_dwordx4 v[88:91], v[34:35], off
	s_xor_b64 s[6:7], s[10:11], -1
	v_or_b32_e32 v176, 8, v173
	v_or_b32_e32 v177, 16, v173
	v_or_b32_e32 v178, 24, v173
	v_add_u32_e32 v179, s0, v117
	s_movk_i32 s0, 0xffc0
	v_mov_b32_e32 v180, v169
	v_lshl_add_u64 v[236:237], v[132:133], 1, v[128:129]
	global_load_dwordx2 v[214:215], v[236:237], off
	global_load_dwordx2 v[216:217], v[236:237], off offset:16
	global_load_dwordx2 v[218:219], v[236:237], off offset:32
	global_load_dwordx2 v[220:221], v[236:237], off offset:48
	global_load_dwordx2 v[222:223], v[236:237], off offset:64
	global_load_dwordx2 v[224:225], v[236:237], off offset:80
	global_load_dwordx2 v[232:233], v[236:237], off offset:96
	global_load_dwordx2 v[234:235], v[236:237], off offset:112
	.p2align	6
